# attention PV: hoist the three serial V-tile LDS reads per k-block (and the partial-block tail reads) into spare VGPRs v228-v239 with counted lgkmcnt(3/2/1/0) so MFMAs overlap LDS latency
# baseline (speedup 1.0000x reference)
; #define LAS __attribute__((address_space(3)))
; __device__ __forceinline__ float shx(float v, int o, int lane) { return __int_as_float(__builtin_amdgcn_ds_bpermute((lane ^ o) << 2, __float_as_int(v))); }
; template <bool EARLY>
; __device__ __forceinline__ void attn_ct(const LAS bf16* Kb, const LAS bf16* Vb, const bf16x8 (&qf)[2], float fd, int rl, int l15, int smin, float slope2, float sink2, int lane, f32x4 (&oacc)[4], float& inv) {
;     constexpr float LOG2E = 1.4426950408889634f;
;     f32x4 sacc[9];
; #pragma unroll
;     for (int kk = 0; kk < 9; ++kk) sacc[kk] = (f32x4){0.f, 0.f, 0.f, 0.f};
; #pragma unroll
;     for (int kk = 0; kk < 9; ++kk)
; #pragma unroll
;         for (int ks = 0; ks < 2; ++ks) { const bf16x8 kf = *(const LAS bf16x8*)(Kb + kk * 16 * 72 + ks * 32);
;             sacc[kk] = __builtin_amdgcn_mfma_f32_16x16x32_bf16(kf, qf[ks], sacc[kk], 0, 0, 0); if (ks == 1 && (kk & 1)) __builtin_amdgcn_sched_barrier(0); }
;     float mx = -1e30f;
; #pragma unroll
;     for (int kk = 0; kk < 9; ++kk)
; #pragma unroll
;         for (int j = 0; j < 4; ++j) { const int rc = kk * 16 + j;
;             float lg = sacc[kk][j] * (0.125f * LOG2E) - slope2 * (fd - (float)rc);
;             if (kk == 0 || kk == 8 || EARLY) { bool ok = true;
;                 if (kk == 0) ok = (rc + rl) > l15;
;                 if (kk == 8) ok = (rc + rl) <= 128 + l15;
;                 if (EARLY) ok = ok && ((rc + rl) >= smin);
;                 lg = ok ? lg : -1e30f; }
;             sacc[kk][j] = lg; mx = fmaxf(mx, lg); }
;     mx = fmaxf(mx, shx(mx, 16, lane)); mx = fmaxf(mx, shx(mx, 32, lane)); mx = fmaxf(mx, sink2);
.LBB0_506:
	v_or_b32_e32 v3, s10, v42
	v_lshlrev_b32_e32 v12, 4, v3
	v_or_b32_e32 v189, s2, v12
	v_or_b32_e32 v38, v189, v40
	v_min_i32_e32 v0, 0x100f, v38
	v_ashrrev_i32_e32 v1, 31, v0
	v_lshl_add_u64 v[0:1], s[8:9], 0, v[0:1]
	s_waitcnt vmcnt(0)
	v_mad_u64_u32 v[4:5], s[10:11], v0, s77, v[36:37]
	v_mov_b32_e32 v0, v5
	v_mad_u64_u32 v[0:1], s[10:11], v1, s77, v[0:1]
	v_mov_b32_e32 v5, v0
	global_load_dwordx4 v[8:11], v[4:5], off offset:2560
	s_nop 0
	global_load_dwordx4 v[4:7], v[4:5], off offset:2624
	v_or_b32_e32 v0, v12, v40
	v_mul_u32_u24_e32 v0, 0x90, v0
	v_lshl_add_u32 v39, v3, 5, v45
	s_and_b64 vcc, exec, s[12:13]
	v_add_u32_e32 v173, v43, v0
	v_add_u32_e32 v171, 0x6800, v39
	v_add_u32_e32 v170, 0x8000, v39
	v_add_u32_e32 v168, 0x9800, v39
	v_add_u32_e32 v166, 0xb000, v39
	s_mov_b64 s[10:11], -1
	s_cbranch_vccz .LBB0_509
	ds_read_b128 v[12:15], v173
	ds_read_b128 v[16:19], v173 offset:64
	s_waitcnt vmcnt(1) lgkmcnt(1)
	v_mfma_f32_16x16x32_bf16 v[12:15], v[12:15], v[8:11], 0
	ds_read_b128 v[20:23], v173 offset:2368
	s_waitcnt vmcnt(0) lgkmcnt(1)
	v_mfma_f32_16x16x32_bf16 v[12:15], v[16:19], v[4:7], v[12:15]
	ds_read_b128 v[16:19], v173 offset:2304
	s_waitcnt lgkmcnt(0)
	v_mfma_f32_16x16x32_bf16 v[16:19], v[16:19], v[8:11], 0
	v_mfma_f32_16x16x32_bf16 v[16:19], v[20:23], v[4:7], v[16:19]
	ds_read_b128 v[20:23], v173 offset:4608
	ds_read_b128 v[24:27], v173 offset:4672
	s_waitcnt lgkmcnt(1)
	v_mfma_f32_16x16x32_bf16 v[20:23], v[20:23], v[8:11], 0
	ds_read_b128 v[190:193], v173 offset:6976
	s_waitcnt lgkmcnt(1)
	v_mfma_f32_16x16x32_bf16 v[20:23], v[24:27], v[4:7], v[20:23]
	ds_read_b128 v[24:27], v173 offset:6912
	s_waitcnt lgkmcnt(0)
	v_mfma_f32_16x16x32_bf16 v[24:27], v[24:27], v[8:11], 0
	v_mfma_f32_16x16x32_bf16 v[24:27], v[190:193], v[4:7], v[24:27]
	ds_read_b128 v[190:193], v173 offset:9216
	ds_read_b128 v[194:197], v173 offset:9280
	s_waitcnt lgkmcnt(1)
	v_mfma_f32_16x16x32_bf16 v[190:193], v[190:193], v[8:11], 0
	ds_read_b128 v[198:201], v173 offset:11584
	s_waitcnt lgkmcnt(1)
	v_mfma_f32_16x16x32_bf16 v[190:193], v[194:197], v[4:7], v[190:193]
	ds_read_b128 v[194:197], v173 offset:11520
	s_waitcnt lgkmcnt(0)
	v_mfma_f32_16x16x32_bf16 v[194:197], v[194:197], v[8:11], 0
	v_mfma_f32_16x16x32_bf16 v[194:197], v[198:201], v[4:7], v[194:197]
	ds_read_b128 v[198:201], v173 offset:13824
	ds_read_b128 v[202:205], v173 offset:13888
	s_waitcnt lgkmcnt(1)
	v_mfma_f32_16x16x32_bf16 v[198:201], v[198:201], v[8:11], 0
	ds_read_b128 v[206:209], v173 offset:16192
	s_waitcnt lgkmcnt(1)
	v_mfma_f32_16x16x32_bf16 v[198:201], v[202:205], v[4:7], v[198:201]
	ds_read_b128 v[202:205], v173 offset:16128
	s_waitcnt lgkmcnt(0)
	v_mfma_f32_16x16x32_bf16 v[202:205], v[202:205], v[8:11], 0
	v_mfma_f32_16x16x32_bf16 v[202:205], v[206:209], v[4:7], v[202:205]
	ds_read_b128 v[206:209], v173 offset:18432
	ds_read_b128 v[210:213], v173 offset:18496
	v_fma_f32 v0, v12, s76, -v33
	v_fma_f32 v1, v13, s76, -v128
	v_fma_f32 v3, v14, s76, -v129
	v_fma_f32 v172, v15, s76, -v130
	v_cndmask_b32_e64 v0, v183, v0, s[38:39]
	v_cndmask_b32_e64 v1, v1, v183, s[40:41]
	s_waitcnt lgkmcnt(1)
	v_mfma_f32_16x16x32_bf16 v[12:15], v[206:209], v[8:11], 0
	v_cndmask_b32_e64 v3, v183, v3, s[42:43]
	v_cndmask_b32_e64 v172, v183, v172, s[44:45]
	v_max3_f32 v206, v0, s86, v1
	v_fma_f32 v16, v16, s76, -v131
	v_fma_f32 v17, v17, s76, -v134
	v_max3_f32 v206, v206, v3, v172
	v_fma_f32 v18, v18, s76, -v135
	v_fma_f32 v19, v19, s76, -v136
	v_max3_f32 v206, v206, v16, v17
	v_fma_f32 v20, v20, s76, -v137
	v_fma_f32 v21, v21, s76, -v138
	v_max3_f32 v206, v206, v18, v19
	v_fma_f32 v22, v22, s76, -v139
	v_fma_f32 v23, v23, s76, -v140
	v_max3_f32 v206, v206, v20, v21
	v_fma_f32 v24, v24, s76, -v141
	v_fma_f32 v25, v25, s76, -v142
	v_max3_f32 v206, v206, v22, v23
	v_fma_f32 v26, v26, s76, -v143
	v_fma_f32 v27, v27, s76, -v144
	v_max3_f32 v206, v206, v24, v25
	v_fma_f32 v190, v190, s76, -v145
	v_fma_f32 v191, v191, s76, -v146
	v_max3_f32 v206, v206, v26, v27
	v_fma_f32 v192, v192, s76, -v147
	v_fma_f32 v193, v193, s76, -v148
	v_max3_f32 v206, v206, v190, v191
	v_fma_f32 v194, v194, s76, -v149
	v_fma_f32 v195, v195, s76, -v150
	v_max3_f32 v206, v206, v192, v193
	s_waitcnt lgkmcnt(0)
	v_mfma_f32_16x16x32_bf16 v[12:15], v[210:213], v[4:7], v[12:15]
	v_fma_f32 v196, v196, s76, -v151
	v_fma_f32 v197, v197, s76, -v152
	v_max3_f32 v206, v206, v194, v195
	v_fma_f32 v198, v198, s76, -v153
	v_fma_f32 v199, v199, s76, -v154
	v_max3_f32 v206, v206, v196, v197
	v_fma_f32 v200, v200, s76, -v155
	v_fma_f32 v201, v201, s76, -v156
	v_max3_f32 v206, v206, v198, v199
	v_fma_f32 v202, v202, s76, -v157
	v_fma_f32 v203, v203, s76, -v158
	v_max3_f32 v206, v206, v200, v201
	v_fma_f32 v204, v204, s76, -v159
	v_fma_f32 v205, v205, s76, -v160
	v_max3_f32 v206, v206, v202, v203
	v_fma_f32 v12, v12, s76, -v161
	v_fma_f32 v13, v13, s76, -v162
	v_max3_f32 v206, v206, v204, v205
	v_cndmask_b32_e64 v12, v183, v12, s[46:47]
	v_cndmask_b32_e64 v13, v183, v13, s[48:49]
	v_fma_f32 v14, v14, s76, -v163
	v_fma_f32 v15, v15, s76, -v164
	v_max3_f32 v206, v206, v12, v13
	v_cndmask_b32_e64 v14, v183, v14, s[50:51]
	v_cndmask_b32_e64 v15, v183, v15, s[52:53]
	v_max3_f32 v206, v206, v14, v15
	ds_bpermute_b32 v207, v84, v206
	s_waitcnt lgkmcnt(0)
	v_max_f32_e32 v207, v207, v207
	v_max_f32_e32 v206, v206, v207
	ds_bpermute_b32 v207, v85, v206
	s_waitcnt lgkmcnt(0)
; #define LAS __attribute__((address_space(3)))
; __device__ __forceinline__ unsigned pk2(float lo, float hi) { return f2bf(lo) | (f2bf(hi) << 16); }
; __device__ __forceinline__ float shx(float v, int o, int lane) { return __int_as_float(__builtin_amdgcn_ds_bpermute((lane ^ o) << 2, __float_as_int(v))); }
; template <bool EARLY>
; __device__ __forceinline__ void attn_ct(const LAS bf16* Kb, const LAS bf16* Vb, const bf16x8 (&qf)[2], float fd, int rl, int l15, int smin, float slope2, float sink2, int lane, f32x4 (&oacc)[4], float& inv) {
;     ...
;     float sum = 0.f;
; #pragma unroll
;     for (int kk = 0; kk < 9; ++kk)
; #pragma unroll
;         for (int j = 0; j < 4; ++j) { const float pe = __builtin_amdgcn_exp2f(sacc[kk][j] - mx); sacc[kk][j] = pe; sum += pe; }
;     sum += shx(sum, 16, lane); sum += shx(sum, 32, lane); sum += __builtin_amdgcn_exp2f(sink2 - mx);
;     inv = 1.0f / sum;
; #pragma unroll
;     for (int dt = 0; dt < 4; ++dt) oacc[dt] = (f32x4){0.f, 0.f, 0.f, 0.f};
; #pragma unroll
;     for (int kb = 0; kb < 5; ++kb) {
;         u32x4 pw; pw.x = pk2(sacc[2 * kb][0], sacc[2 * kb][1]); pw.y = pk2(sacc[2 * kb][2], sacc[2 * kb][3]);
;         if (2 * kb + 1 < 9) { pw.z = pk2(sacc[2 * kb + 1][0], sacc[2 * kb + 1][1]); pw.w = pk2(sacc[2 * kb + 1][2], sacc[2 * kb + 1][3]); } else { pw.z = 0u; pw.w = 0u; }
;         const bf16x8 pf = __builtin_bit_cast(bf16x8, pw);
; #pragma unroll
;         for (int dt = 0; dt < 4; ++dt) { const LAS bf16* vp = Vb + dt * 16 * 200 + kb * 32;
;             const u32x2 lo = *(const LAS u32x2*)vp; u32x2 hi = (u32x2){0u, 0u}; if (2 * kb + 1 < 9) hi = *(const LAS u32x2*)(vp + 16);
;             u32x4 w; w.x = lo.x; w.y = lo.y; w.z = hi.x; w.w = hi.y; const bf16x8 vf = __builtin_bit_cast(bf16x8, w);
;             oacc[dt] = __builtin_amdgcn_mfma_f32_16x16x32_bf16(vf, pf, oacc[dt], 0, 0, 0); }
	v_max3_f32 v206, v206, v207, v165
	v_sub_f32_e32 v0, v0, v206
	v_exp_f32_e32 v0, v0
	v_sub_f32_e32 v1, v1, v206
	v_exp_f32_e32 v1, v1
	v_sub_f32_e32 v3, v3, v206
	v_exp_f32_e32 v3, v3
	v_sub_f32_e32 v172, v172, v206
	v_exp_f32_e32 v172, v172
	v_sub_f32_e32 v16, v16, v206
	v_add_f32_e32 v207, 0, v0
	v_exp_f32_e32 v16, v16
	v_sub_f32_e32 v17, v17, v206
	v_add_f32_e32 v207, v1, v207
	v_exp_f32_e32 v17, v17
	v_sub_f32_e32 v18, v18, v206
	v_add_f32_e32 v207, v3, v207
	v_exp_f32_e32 v18, v18
	v_sub_f32_e32 v19, v19, v206
	v_add_f32_e32 v207, v172, v207
	v_exp_f32_e32 v19, v19
	v_sub_f32_e32 v20, v20, v206
	v_add_f32_e32 v207, v16, v207
	v_exp_f32_e32 v208, v20
	v_sub_f32_e32 v20, v21, v206
	v_add_f32_e32 v207, v17, v207
	v_exp_f32_e32 v209, v20
	v_sub_f32_e32 v20, v22, v206
	v_add_f32_e32 v207, v18, v207
	v_exp_f32_e32 v210, v20
	v_sub_f32_e32 v20, v23, v206
	v_add_f32_e32 v207, v19, v207
	v_exp_f32_e32 v211, v20
	v_sub_f32_e32 v21, v24, v206
	v_add_f32_e32 v20, v208, v207
	v_exp_f32_e32 v207, v21
	v_sub_f32_e32 v21, v25, v206
	v_add_f32_e32 v20, v209, v20
	v_exp_f32_e32 v212, v21
	v_sub_f32_e32 v21, v26, v206
	v_add_f32_e32 v20, v210, v20
	v_exp_f32_e32 v213, v21
	v_sub_f32_e32 v21, v27, v206
	v_add_f32_e32 v20, v211, v20
	v_exp_f32_e32 v214, v21
	v_sub_f32_e32 v21, v190, v206
	v_add_f32_e32 v20, v207, v20
	v_exp_f32_e32 v215, v21
	v_sub_f32_e32 v21, v191, v206
	v_add_f32_e32 v20, v212, v20
	v_exp_f32_e32 v216, v21
	v_sub_f32_e32 v21, v192, v206
	v_add_f32_e32 v20, v213, v20
	v_exp_f32_e32 v217, v21
	v_sub_f32_e32 v21, v193, v206
	v_add_f32_e32 v20, v214, v20
	v_exp_f32_e32 v218, v21
	v_sub_f32_e32 v21, v194, v206
	v_add_f32_e32 v20, v215, v20
	v_exp_f32_e32 v219, v21
	v_sub_f32_e32 v21, v195, v206
	v_add_f32_e32 v20, v216, v20
	v_exp_f32_e32 v220, v21
	v_sub_f32_e32 v21, v196, v206
	v_add_f32_e32 v20, v217, v20
	v_exp_f32_e32 v221, v21
	v_sub_f32_e32 v21, v197, v206
	v_add_f32_e32 v20, v218, v20
	v_exp_f32_e32 v222, v21
	v_sub_f32_e32 v21, v198, v206
	v_add_f32_e32 v20, v219, v20
	v_exp_f32_e32 v198, v21
	v_sub_f32_e32 v21, v199, v206
	v_add_f32_e32 v20, v220, v20
	v_exp_f32_e32 v199, v21
	v_sub_f32_e32 v21, v200, v206
	v_add_f32_e32 v20, v221, v20
	v_exp_f32_e32 v200, v21
	v_sub_f32_e32 v21, v201, v206
	v_add_f32_e32 v20, v222, v20
	v_exp_f32_e32 v201, v21
	v_sub_f32_e32 v21, v202, v206
	v_add_f32_e32 v20, v198, v20
	v_exp_f32_e32 v202, v21
	v_sub_f32_e32 v21, v203, v206
	v_add_f32_e32 v20, v199, v20
	v_exp_f32_e32 v203, v21
	v_sub_f32_e32 v21, v204, v206
	v_add_f32_e32 v20, v200, v20
	v_exp_f32_e32 v204, v21
	v_sub_f32_e32 v21, v205, v206
	v_add_f32_e32 v20, v201, v20
	v_exp_f32_e32 v205, v21
	v_sub_f32_e32 v12, v12, v206
	v_add_f32_e32 v20, v202, v20
	v_exp_f32_e32 v223, v12
	v_sub_f32_e32 v12, v13, v206
	v_add_f32_e32 v20, v203, v20
	v_exp_f32_e32 v224, v12
	v_sub_f32_e32 v12, v14, v206
	v_add_f32_e32 v20, v204, v20
	v_exp_f32_e32 v225, v12
	v_sub_f32_e32 v12, v15, v206
	v_add_f32_e32 v20, v205, v20
	v_exp_f32_e32 v226, v12
	v_add_f32_e32 v12, v223, v20
	v_add_f32_e32 v12, v224, v12
	v_add_f32_e32 v12, v225, v12
	v_add_f32_e32 v190, v226, v12
	ds_bpermute_b32 v191, v84, v190
	v_bfe_u32 v12, v19, 16, 1
	v_bfe_u32 v13, v17, 16, 1
	v_bfe_u32 v14, v172, 16, 1
	v_bfe_u32 v15, v1, 16, 1
	v_add3_u32 v1, v1, v15, s88
	v_add3_u32 v24, v172, v14, s88
	v_add3_u32 v17, v17, v13, s88
	v_add3_u32 v19, v19, v12, s88
	v_bfe_u32 v12, v0, 16, 1
	v_bfe_u32 v13, v3, 16, 1
	v_bfe_u32 v14, v16, 16, 1
	v_bfe_u32 v15, v18, 16, 1
	v_add3_u32 v18, v18, v15, s88
	v_add3_u32 v16, v16, v14, s88
	v_add3_u32 v3, v3, v13, s88
	v_add3_u32 v0, v0, v12, s88
	v_lshrrev_b32_e32 v0, 16, v0
	v_lshrrev_b32_e32 v3, 16, v3
	v_lshrrev_b32_e32 v16, 16, v16
	v_lshrrev_b32_e32 v18, 16, v18
	ds_read2_b64 v[12:15], v171 offset0:128 offset1:132
	v_and_or_b32 v19, v19, s3, v18
	v_and_or_b32 v18, v17, s3, v16
	ds_read2_b64 v[20:23], v170 offset0:160 offset1:164
	v_and_or_b32 v17, v24, s3, v3
	v_and_or_b32 v16, v1, s3, v0
	ds_read2_b64 v[24:27], v168 offset0:192 offset1:196
	s_waitcnt lgkmcnt(3)
	v_add_f32_e32 v0, v190, v191
	ds_read2_b64 v[190:193], v166 offset0:224 offset1:228
	ds_bpermute_b32 v1, v85, v0
	v_sub_f32_e32 v3, v165, v206
	v_exp_f32_e32 v3, v3
	s_waitcnt lgkmcnt(4)
	v_mfma_f32_16x16x32_bf16 v[12:15], v[12:15], v[16:19], 0
	s_waitcnt lgkmcnt(0)
	v_add_f32_e32 v0, v0, v1
	v_add_f32_e32 v172, v3, v0
	v_mfma_f32_16x16x32_bf16 v[20:23], v[20:23], v[16:19], 0
	v_mfma_f32_16x16x32_bf16 v[24:27], v[24:27], v[16:19], 0
	v_mfma_f32_16x16x32_bf16 v[16:19], v[190:193], v[16:19], 0
	v_bfe_u32 v190, v209, 16, 1
	v_add3_u32 v194, v209, v190, s88
	v_bfe_u32 v190, v208, 16, 1
	v_bfe_u32 v191, v210, 16, 1
	v_bfe_u32 v192, v207, 16, 1
	v_bfe_u32 v193, v213, 16, 1
	v_add3_u32 v195, v213, v193, s88
	v_add3_u32 v196, v207, v192, s88
	v_add3_u32 v197, v210, v191, s88
	v_add3_u32 v206, v208, v190, s88
	ds_read2_b64 v[190:193], v171 offset0:136 offset1:140
	ds_read2_b64 v[228:231], v170 offset0:168 offset1:172
	ds_read2_b64 v[232:235], v168 offset0:200 offset1:204
	ds_read2_b64 v[236:239], v166 offset0:232 offset1:236
	v_bfe_u32 v0, v214, 16, 1
	v_bfe_u32 v1, v212, 16, 1
	v_bfe_u32 v3, v211, 16, 1
	v_add3_u32 v3, v211, v3, s88
	v_add3_u32 v1, v212, v1, s88
	v_add3_u32 v0, v214, v0, s88
	v_lshrrev_b32_e32 v206, 16, v206
	v_lshrrev_b32_e32 v207, 16, v197
	v_lshrrev_b32_e32 v196, 16, v196
	v_lshrrev_b32_e32 v195, 16, v195
	v_and_or_b32 v197, v0, s3, v195
	v_and_or_b32 v196, v1, s3, v196
	v_and_or_b32 v195, v3, s3, v207
	v_and_or_b32 v194, v194, s3, v206
	s_waitcnt lgkmcnt(3)
; #define LAS __attribute__((address_space(3)))
; __device__ __forceinline__ unsigned pk2(float lo, float hi) { return f2bf(lo) | (f2bf(hi) << 16); }
; template <bool EARLY>
; __device__ __forceinline__ void attn_ct(const LAS bf16* Kb, const LAS bf16* Vb, const bf16x8 (&qf)[2], float fd, int rl, int l15, int smin, float slope2, float sink2, int lane, f32x4 (&oacc)[4], float& inv) {
;     ...
;     for (int kb = 0; kb < 5; ++kb) {
;         u32x4 pw; pw.x = pk2(sacc[2 * kb][0], sacc[2 * kb][1]); pw.y = pk2(sacc[2 * kb][2], sacc[2 * kb][3]);
;         if (2 * kb + 1 < 9) { pw.z = pk2(sacc[2 * kb + 1][0], sacc[2 * kb + 1][1]); pw.w = pk2(sacc[2 * kb + 1][2], sacc[2 * kb + 1][3]); } else { pw.z = 0u; pw.w = 0u; }
;         const bf16x8 pf = __builtin_bit_cast(bf16x8, pw);
; #pragma unroll
;         for (int dt = 0; dt < 4; ++dt) { const LAS bf16* vp = Vb + dt * 16 * 200 + kb * 32;
;             const u32x2 lo = *(const LAS u32x2*)vp; u32x2 hi = (u32x2){0u, 0u}; if (2 * kb + 1 < 9) hi = *(const LAS u32x2*)(vp + 16);
;             u32x4 w; w.x = lo.x; w.y = lo.y; w.z = hi.x; w.w = hi.y; const bf16x8 vf = __builtin_bit_cast(bf16x8, w);
;             oacc[dt] = __builtin_amdgcn_mfma_f32_16x16x32_bf16(vf, pf, oacc[dt], 0, 0, 0); }
;         __builtin_amdgcn_sched_barrier(0);
;     }
	s_nop 0
	v_mfma_f32_16x16x32_bf16 v[12:15], v[190:193], v[194:197], v[12:15]
	s_waitcnt lgkmcnt(2)
	v_mfma_f32_16x16x32_bf16 v[20:23], v[228:231], v[194:197], v[20:23]
	s_waitcnt lgkmcnt(1)
	v_mfma_f32_16x16x32_bf16 v[24:27], v[232:235], v[194:197], v[24:27]
	s_waitcnt lgkmcnt(0)
	v_mfma_f32_16x16x32_bf16 v[16:19], v[236:239], v[194:197], v[16:19]
	v_bfe_u32 v190, v216, 16, 1
	v_add3_u32 v194, v216, v190, s88
	v_bfe_u32 v190, v215, 16, 1
	v_bfe_u32 v191, v217, 16, 1
	v_bfe_u32 v192, v219, 16, 1
	v_bfe_u32 v193, v221, 16, 1
	v_add3_u32 v195, v221, v193, s88
	v_add3_u32 v196, v219, v192, s88
	v_add3_u32 v197, v217, v191, s88
	v_add3_u32 v206, v215, v190, s88
	ds_read2_b64 v[190:193], v171 offset0:144 offset1:148
	ds_read2_b64 v[228:231], v170 offset0:176 offset1:180
	ds_read2_b64 v[232:235], v168 offset0:208 offset1:212
	ds_read2_b64 v[236:239], v166 offset0:240 offset1:244
	v_bfe_u32 v0, v222, 16, 1
	v_bfe_u32 v1, v220, 16, 1
	v_bfe_u32 v3, v218, 16, 1
	v_add3_u32 v3, v218, v3, s88
	v_add3_u32 v1, v220, v1, s88
	v_add3_u32 v0, v222, v0, s88
	v_lshrrev_b32_e32 v206, 16, v206
	v_lshrrev_b32_e32 v207, 16, v197
	v_lshrrev_b32_e32 v196, 16, v196
	v_lshrrev_b32_e32 v195, 16, v195
	v_and_or_b32 v197, v0, s3, v195
	v_and_or_b32 v196, v1, s3, v196
	v_and_or_b32 v195, v3, s3, v207
	v_and_or_b32 v194, v194, s3, v206
	s_waitcnt lgkmcnt(3)
	s_nop 0
	v_mfma_f32_16x16x32_bf16 v[12:15], v[190:193], v[194:197], v[12:15]
	s_waitcnt lgkmcnt(2)
	v_mfma_f32_16x16x32_bf16 v[20:23], v[228:231], v[194:197], v[20:23]
	s_waitcnt lgkmcnt(1)
	v_mfma_f32_16x16x32_bf16 v[24:27], v[232:235], v[194:197], v[24:27]
	s_waitcnt lgkmcnt(0)
	v_mfma_f32_16x16x32_bf16 v[16:19], v[236:239], v[194:197], v[16:19]
	v_bfe_u32 v190, v199, 16, 1
	v_add3_u32 v194, v199, v190, s88
	v_bfe_u32 v190, v198, 16, 1
	v_bfe_u32 v191, v200, 16, 1
	v_bfe_u32 v192, v202, 16, 1
	v_bfe_u32 v193, v204, 16, 1
	v_add3_u32 v195, v204, v193, s88
	v_add3_u32 v196, v202, v192, s88
	v_add3_u32 v197, v200, v191, s88
	v_add3_u32 v198, v198, v190, s88
	ds_read2_b64 v[190:193], v171 offset0:152 offset1:156
	ds_read2_b64 v[228:231], v170 offset0:184 offset1:188
	ds_read2_b64 v[232:235], v168 offset0:216 offset1:220
	ds_read2_b64 v[236:239], v166 offset0:248 offset1:252
	v_bfe_u32 v0, v205, 16, 1
	v_bfe_u32 v1, v203, 16, 1
	v_bfe_u32 v3, v201, 16, 1
	v_add3_u32 v3, v201, v3, s88
	v_add3_u32 v1, v203, v1, s88
	v_add3_u32 v0, v205, v0, s88
	v_lshrrev_b32_e32 v198, 16, v198
	v_lshrrev_b32_e32 v199, 16, v197
	v_lshrrev_b32_e32 v196, 16, v196
	v_lshrrev_b32_e32 v195, 16, v195
	v_and_or_b32 v197, v0, s3, v195
	v_and_or_b32 v196, v1, s3, v196
	v_and_or_b32 v195, v3, s3, v199
	v_and_or_b32 v194, v194, s3, v198
	s_waitcnt lgkmcnt(3)
	s_nop 0
	v_mfma_f32_16x16x32_bf16 v[12:15], v[190:193], v[194:197], v[12:15]
	s_waitcnt lgkmcnt(2)
	v_mfma_f32_16x16x32_bf16 v[20:23], v[228:231], v[194:197], v[20:23]
	s_waitcnt lgkmcnt(1)
	v_mfma_f32_16x16x32_bf16 v[24:27], v[232:235], v[194:197], v[24:27]
	s_waitcnt lgkmcnt(0)
	v_mfma_f32_16x16x32_bf16 v[190:193], v[236:239], v[194:197], v[16:19]
	v_and_b32_sdwa v1, v224, v174 dst_sel:DWORD dst_unused:UNUSED_PAD src0_sel:WORD_1 src1_sel:DWORD
	v_and_b32_sdwa v0, v226, v174 dst_sel:DWORD dst_unused:UNUSED_PAD src0_sel:WORD_1 src1_sel:DWORD
	v_add3_u32 v1, v224, v1, s88
	v_add3_u32 v0, v226, v0, s88
	v_and_b32_e32 v3, 0xffff0000, v1
	v_and_b32_sdwa v1, v225, v174 dst_sel:DWORD dst_unused:UNUSED_PAD src0_sel:WORD_1 src1_sel:DWORD
	v_and_b32_sdwa v16, v223, v174 dst_sel:DWORD dst_unused:UNUSED_PAD src0_sel:WORD_1 src1_sel:DWORD
	v_and_b32_e32 v0, 0xffff0000, v0
	v_add3_u32 v16, v223, v16, s88
	v_add3_u32 v1, v225, v1, s88
	v_or_b32_sdwa v1, v0, v1 dst_sel:DWORD dst_unused:UNUSED_PAD src0_sel:DWORD src1_sel:WORD_1
	v_or_b32_sdwa v0, v3, v16 dst_sel:DWORD dst_unused:UNUSED_PAD src0_sel:DWORD src1_sel:WORD_1
	ds_read_b64 v[16:17], v39 offset:27904
	ds_read_b64 v[228:229], v39 offset:34304
	ds_read_b64 v[232:233], v39 offset:40704
	ds_read_b64 v[236:237], v39 offset:47104
	v_mov_b32_e32 v18, v2
	v_mov_b32_e32 v19, v2
	v_mov_b32_e32 v3, v2
	v_mov_b32_e32 v230, v2
	v_mov_b32_e32 v231, v2
	v_mov_b32_e32 v234, v2
	v_mov_b32_e32 v235, v2
	v_mov_b32_e32 v238, v2
	v_mov_b32_e32 v239, v2
	s_waitcnt lgkmcnt(3)
	s_nop 0
	v_mfma_f32_16x16x32_bf16 v[16:19], v[16:19], v[0:3], v[12:15]
	s_waitcnt lgkmcnt(2)
	v_mfma_f32_16x16x32_bf16 v[20:23], v[228:231], v[0:3], v[20:23]
	s_waitcnt lgkmcnt(1)
	v_mfma_f32_16x16x32_bf16 v[12:15], v[232:235], v[0:3], v[24:27]
	s_waitcnt lgkmcnt(0)
	v_mfma_f32_16x16x32_bf16 v[24:27], v[236:239], v[0:3], v[190:193]
	s_cbranch_execz .LBB0_510

; #define LAS __attribute__((address_space(3)))
; __device__ __forceinline__ float shx(float v, int o, int lane) { return __int_as_float(__builtin_amdgcn_ds_bpermute((lane ^ o) << 2, __float_as_int(v))); }
; template <bool EARLY>
; __device__ __forceinline__ void attn_ct(const LAS bf16* Kb, const LAS bf16* Vb, const bf16x8 (&qf)[2], float fd, int rl, int l15, int smin, float slope2, float sink2, int lane, f32x4 (&oacc)[4], float& inv) {
;     ...
;     for (int kk = 0; kk < 9; ++kk)
; #pragma unroll
;         for (int ks = 0; ks < 2; ++ks) { const bf16x8 kf = *(const LAS bf16x8*)(Kb + kk * 16 * 72 + ks * 32);
;             sacc[kk] = __builtin_amdgcn_mfma_f32_16x16x32_bf16(kf, qf[ks], sacc[kk], 0, 0, 0); if (ks == 1 && (kk & 1)) __builtin_amdgcn_sched_barrier(0); }
;     float mx = -1e30f;
; #pragma unroll
;     for (int kk = 0; kk < 9; ++kk)
; #pragma unroll
;         for (int j = 0; j < 4; ++j) { const int rc = kk * 16 + j;
;             float lg = sacc[kk][j] * (0.125f * LOG2E) - slope2 * (fd - (float)rc);
;             if (kk == 0 || kk == 8 || EARLY) { bool ok = true;
;                 if (kk == 0) ok = (rc + rl) > l15;
;                 if (kk == 8) ok = (rc + rl) <= 128 + l15;
;                 if (EARLY) ok = ok && ((rc + rl) >= smin);
;                 lg = ok ? lg : -1e30f; }
;             sacc[kk][j] = lg; mx = fmaxf(mx, lg); }
;     mx = fmaxf(mx, shx(mx, 16, lane)); mx = fmaxf(mx, shx(mx, 32, lane)); mx = fmaxf(mx, sink2);
.LBB0_510:
	ds_read_b128 v[12:15], v173
	ds_read_b128 v[16:19], v173 offset:64
	v_sub_u32_e32 v0, 0x80, v189
	s_waitcnt vmcnt(1) lgkmcnt(1)
	v_mfma_f32_16x16x32_bf16 v[12:15], v[12:15], v[8:11], 0
	ds_read_b128 v[20:23], v173 offset:2368
	s_waitcnt vmcnt(0) lgkmcnt(1)
	v_mfma_f32_16x16x32_bf16 v[12:15], v[16:19], v[4:7], v[12:15]
	ds_read_b128 v[16:19], v173 offset:2304
	s_waitcnt lgkmcnt(0)
	v_mfma_f32_16x16x32_bf16 v[16:19], v[16:19], v[8:11], 0
	v_mfma_f32_16x16x32_bf16 v[16:19], v[20:23], v[4:7], v[16:19]
	ds_read_b128 v[20:23], v173 offset:4608
	ds_read_b128 v[24:27], v173 offset:4672
	s_waitcnt lgkmcnt(1)
	v_mfma_f32_16x16x32_bf16 v[20:23], v[20:23], v[8:11], 0
	ds_read_b128 v[190:193], v173 offset:6976
	s_waitcnt lgkmcnt(1)
	v_mfma_f32_16x16x32_bf16 v[20:23], v[24:27], v[4:7], v[20:23]
	ds_read_b128 v[24:27], v173 offset:6912
	s_waitcnt lgkmcnt(0)
	v_mfma_f32_16x16x32_bf16 v[24:27], v[24:27], v[8:11], 0
	v_mfma_f32_16x16x32_bf16 v[24:27], v[190:193], v[4:7], v[24:27]
	ds_read_b128 v[190:193], v173 offset:9216
	ds_read_b128 v[194:197], v173 offset:9280
	s_waitcnt lgkmcnt(1)
	v_mfma_f32_16x16x32_bf16 v[190:193], v[190:193], v[8:11], 0
	ds_read_b128 v[198:201], v173 offset:11584
	s_waitcnt lgkmcnt(1)
	v_mfma_f32_16x16x32_bf16 v[190:193], v[194:197], v[4:7], v[190:193]
	ds_read_b128 v[194:197], v173 offset:11520
	s_waitcnt lgkmcnt(0)
	v_mfma_f32_16x16x32_bf16 v[194:197], v[194:197], v[8:11], 0
	v_mfma_f32_16x16x32_bf16 v[194:197], v[198:201], v[4:7], v[194:197]
	ds_read_b128 v[198:201], v173 offset:13824
	ds_read_b128 v[202:205], v173 offset:13888
	s_waitcnt lgkmcnt(1)
	v_mfma_f32_16x16x32_bf16 v[198:201], v[198:201], v[8:11], 0
	ds_read_b128 v[206:209], v173 offset:16192
	s_waitcnt lgkmcnt(1)
	v_mfma_f32_16x16x32_bf16 v[198:201], v[202:205], v[4:7], v[198:201]
	ds_read_b128 v[202:205], v173 offset:16128
	s_waitcnt lgkmcnt(0)
	v_mfma_f32_16x16x32_bf16 v[202:205], v[202:205], v[8:11], 0
	v_mfma_f32_16x16x32_bf16 v[202:205], v[206:209], v[4:7], v[202:205]
	ds_read_b128 v[206:209], v173 offset:18432
	v_cmp_ge_i32_e32 vcc, v44, v0
	v_fma_f32 v1, v12, s76, -v33
	s_and_b64 vcc, s[38:39], vcc
	v_cndmask_b32_e32 v1, v183, v1, vcc
	v_cmp_lt_i32_e32 vcc, v86, v0
	v_fma_f32 v3, v13, s76, -v128
	s_or_b64 vcc, s[40:41], vcc
	v_cndmask_b32_e32 v3, v3, v183, vcc
	s_waitcnt lgkmcnt(0)
	v_mfma_f32_16x16x32_bf16 v[8:11], v[206:209], v[8:11], 0
	ds_read_b128 v[206:209], v173 offset:18496
	v_cmp_ge_i32_e32 vcc, v49, v0
	s_and_b64 vcc, s[42:43], vcc
	v_fma_f32 v12, v17, s76, -v134
	v_fma_f32 v13, v18, s76, -v135
	v_fma_f32 v17, v22, s76, -v139
	v_fma_f32 v18, v23, s76, -v140
	v_fma_f32 v22, v27, s76, -v144
	s_waitcnt lgkmcnt(0)
	v_mfma_f32_16x16x32_bf16 v[4:7], v[206:209], v[4:7], v[8:11]
	v_fma_f32 v23, v190, s76, -v145
	v_fma_f32 v27, v194, s76, -v149
	s_nop 0
	v_fma_f32 v9, v14, s76, -v129
	v_cndmask_b32_e32 v9, v183, v9, vcc
	v_cmp_ge_i32_e32 vcc, v51, v0
	v_fma_f32 v10, v15, s76, -v130
	s_and_b64 vcc, s[44:45], vcc
	v_cndmask_b32_e32 v10, v183, v10, vcc
	v_fma_f32 v11, v16, s76, -v131
	v_cmp_ge_i32_e32 vcc, v87, v0
	v_fma_f32 v14, v19, s76, -v136
	v_fma_f32 v15, v20, s76, -v137
	v_cndmask_b32_e32 v11, v183, v11, vcc
	v_cmp_ge_i32_e32 vcc, v88, v0
	v_fma_f32 v16, v21, s76, -v138
	v_fma_f32 v19, v24, s76, -v141
	v_cndmask_b32_e32 v12, v183, v12, vcc
	v_cmp_ge_i32_e32 vcc, v89, v0
	v_fma_f32 v20, v25, s76, -v142
	v_fma_f32 v21, v26, s76, -v143
	v_cndmask_b32_e32 v13, v183, v13, vcc
	v_cmp_ge_i32_e32 vcc, v90, v0
	v_fma_f32 v24, v191, s76, -v146
	v_fma_f32 v25, v192, s76, -v147
	v_cndmask_b32_e32 v14, v183, v14, vcc
	v_cmp_ge_i32_e32 vcc, v91, v0
	v_fma_f32 v26, v193, s76, -v148
	v_fma_f32 v172, v195, s76, -v150
	v_cndmask_b32_e32 v15, v183, v15, vcc
	v_cmp_ge_i32_e32 vcc, v92, v0
	v_fma_f32 v173, v196, s76, -v151
	v_fma_f32 v189, v197, s76, -v152
	v_cndmask_b32_e32 v16, v183, v16, vcc
	v_cmp_ge_i32_e32 vcc, v93, v0
	v_max3_f32 v8, v1, s86, v3
	v_fma_f32 v190, v198, s76, -v153
	v_cndmask_b32_e32 v17, v183, v17, vcc
	v_cmp_ge_i32_e32 vcc, v94, v0
	v_max3_f32 v8, v8, v9, v10
	v_fma_f32 v191, v199, s76, -v154
	v_cndmask_b32_e32 v18, v183, v18, vcc
	v_cmp_ge_i32_e32 vcc, v95, v0
	v_max3_f32 v8, v8, v11, v12
	v_fma_f32 v192, v200, s76, -v155
	v_cndmask_b32_e32 v19, v183, v19, vcc
	v_cmp_ge_i32_e32 vcc, v96, v0
	v_max3_f32 v8, v8, v13, v14
	v_fma_f32 v193, v201, s76, -v156
	v_cndmask_b32_e32 v20, v183, v20, vcc
	v_cmp_ge_i32_e32 vcc, v97, v0
	v_max3_f32 v8, v8, v15, v16
	v_fma_f32 v194, v202, s76, -v157
	v_cndmask_b32_e32 v21, v183, v21, vcc
	v_cmp_ge_i32_e32 vcc, v98, v0
	v_max3_f32 v8, v8, v17, v18
	v_fma_f32 v195, v203, s76, -v158
	v_cndmask_b32_e32 v22, v183, v22, vcc
	v_cmp_ge_i32_e32 vcc, v99, v0
	v_max3_f32 v8, v8, v19, v20
	v_fma_f32 v196, v204, s76, -v159
	v_cndmask_b32_e32 v23, v183, v23, vcc
	v_cmp_ge_i32_e32 vcc, v100, v0
	v_max3_f32 v8, v8, v21, v22
	v_fma_f32 v197, v205, s76, -v160
	v_cndmask_b32_e32 v24, v183, v24, vcc
	v_cmp_ge_i32_e32 vcc, v101, v0
	v_max3_f32 v8, v8, v23, v24
	v_fma_f32 v4, v4, s76, -v161
	v_cndmask_b32_e32 v25, v183, v25, vcc
	v_cmp_ge_i32_e32 vcc, v102, v0
	v_fma_f32 v5, v5, s76, -v162
	v_fma_f32 v6, v6, s76, -v163
	v_cndmask_b32_e32 v26, v183, v26, vcc
	v_cmp_ge_i32_e32 vcc, v103, v0
	v_max3_f32 v8, v8, v25, v26
	v_fma_f32 v7, v7, s76, -v164
	v_cndmask_b32_e32 v27, v183, v27, vcc
	v_cmp_ge_i32_e32 vcc, v104, v0
	s_nop 1
	v_cndmask_b32_e32 v172, v183, v172, vcc
	v_cmp_ge_i32_e32 vcc, v105, v0
	v_max3_f32 v8, v8, v27, v172
	s_nop 0
	v_cndmask_b32_e32 v173, v183, v173, vcc
	v_cmp_ge_i32_e32 vcc, v106, v0
	s_nop 1
	v_cndmask_b32_e32 v189, v183, v189, vcc
	v_cmp_ge_i32_e32 vcc, v107, v0
	v_max3_f32 v8, v8, v173, v189
	s_nop 0
	v_cndmask_b32_e32 v190, v183, v190, vcc
	v_cmp_ge_i32_e32 vcc, v108, v0
	s_nop 1
	v_cndmask_b32_e32 v191, v183, v191, vcc
	v_cmp_ge_i32_e32 vcc, v109, v0
	v_max3_f32 v8, v8, v190, v191
	s_nop 0
	v_cndmask_b32_e32 v192, v183, v192, vcc
	v_cmp_ge_i32_e32 vcc, v110, v0
	s_nop 1
	v_cndmask_b32_e32 v193, v183, v193, vcc
	v_cmp_ge_i32_e32 vcc, v111, v0
	v_max3_f32 v8, v8, v192, v193
	s_nop 0
	v_cndmask_b32_e32 v194, v183, v194, vcc
	v_cmp_ge_i32_e32 vcc, v112, v0
	s_nop 1
	v_cndmask_b32_e32 v195, v183, v195, vcc
	v_cmp_ge_i32_e32 vcc, v113, v0
	v_max3_f32 v8, v8, v194, v195
	s_nop 0
	v_cndmask_b32_e32 v196, v183, v196, vcc
	v_cmp_ge_i32_e32 vcc, v114, v0
	s_nop 1
	v_cndmask_b32_e32 v197, v183, v197, vcc
	v_cmp_lt_i32_e32 vcc, v115, v0
	s_or_b64 vcc, s[38:39], vcc
	v_max3_f32 v8, v8, v196, v197
	v_cndmask_b32_e32 v4, v4, v183, vcc
	v_cmp_lt_i32_e32 vcc, v116, v0
	s_or_b64 vcc, s[54:55], vcc
	s_nop 0
	v_cndmask_b32_e32 v5, v5, v183, vcc
	v_cmp_lt_i32_e32 vcc, v117, v0
	s_or_b64 vcc, s[56:57], vcc
	v_max3_f32 v8, v8, v4, v5
	v_cndmask_b32_e32 v6, v6, v183, vcc
	v_cmp_lt_i32_e32 vcc, v118, v0
	s_or_b64 vcc, s[58:59], vcc
	s_nop 0
	v_cndmask_b32_e32 v0, v7, v183, vcc
	v_max3_f32 v7, v8, v6, v0
	ds_bpermute_b32 v8, v84, v7
	s_waitcnt lgkmcnt(0)
; #define LAS __attribute__((address_space(3)))
; __device__ __forceinline__ unsigned pk2(float lo, float hi) { return f2bf(lo) | (f2bf(hi) << 16); }
; __device__ __forceinline__ float shx(float v, int o, int lane) { return __int_as_float(__builtin_amdgcn_ds_bpermute((lane ^ o) << 2, __float_as_int(v))); }
; template <bool EARLY>
; __device__ __forceinline__ void attn_ct(const LAS bf16* Kb, const LAS bf16* Vb, const bf16x8 (&qf)[2], float fd, int rl, int l15, int smin, float slope2, float sink2, int lane, f32x4 (&oacc)[4], float& inv) {
;     ...
;     mx = fmaxf(mx, shx(mx, 16, lane)); mx = fmaxf(mx, shx(mx, 32, lane)); mx = fmaxf(mx, sink2);
;     float sum = 0.f;
; #pragma unroll
;     for (int kk = 0; kk < 9; ++kk)
; #pragma unroll
;         for (int j = 0; j < 4; ++j) { const float pe = __builtin_amdgcn_exp2f(sacc[kk][j] - mx); sacc[kk][j] = pe; sum += pe; }
;     sum += shx(sum, 16, lane); sum += shx(sum, 32, lane); sum += __builtin_amdgcn_exp2f(sink2 - mx);
;     inv = 1.0f / sum;
; #pragma unroll
;     for (int dt = 0; dt < 4; ++dt) oacc[dt] = (f32x4){0.f, 0.f, 0.f, 0.f};
; #pragma unroll
;     for (int kb = 0; kb < 5; ++kb) {
;         u32x4 pw; pw.x = pk2(sacc[2 * kb][0], sacc[2 * kb][1]); pw.y = pk2(sacc[2 * kb][2], sacc[2 * kb][3]);
;         if (2 * kb + 1 < 9) { pw.z = pk2(sacc[2 * kb + 1][0], sacc[2 * kb + 1][1]); pw.w = pk2(sacc[2 * kb + 1][2], sacc[2 * kb + 1][3]); } else { pw.z = 0u; pw.w = 0u; }
;         const bf16x8 pf = __builtin_bit_cast(bf16x8, pw);
; #pragma unroll
;         for (int dt = 0; dt < 4; ++dt) { const LAS bf16* vp = Vb + dt * 16 * 200 + kb * 32;
;             const u32x2 lo = *(const LAS u32x2*)vp; u32x2 hi = (u32x2){0u, 0u}; if (2 * kb + 1 < 9) hi = *(const LAS u32x2*)(vp + 16);
;             u32x4 w; w.x = lo.x; w.y = lo.y; w.z = hi.x; w.w = hi.y; const bf16x8 vf = __builtin_bit_cast(bf16x8, w);
;             oacc[dt] = __builtin_amdgcn_mfma_f32_16x16x32_bf16(vf, pf, oacc[dt], 0, 0, 0); }
;         __builtin_amdgcn_sched_barrier(0);
;     }
	v_max_f32_e32 v8, v8, v8
	v_max_f32_e32 v7, v7, v8
	ds_bpermute_b32 v8, v85, v7
	s_waitcnt lgkmcnt(0)
	v_max3_f32 v7, v7, v8, v165
	v_sub_f32_e32 v1, v1, v7
	v_exp_f32_e32 v1, v1
	v_sub_f32_e32 v3, v3, v7
	v_exp_f32_e32 v3, v3
	v_sub_f32_e32 v9, v9, v7
	v_exp_f32_e32 v9, v9
	v_sub_f32_e32 v10, v10, v7
	v_exp_f32_e32 v10, v10
	v_sub_f32_e32 v11, v11, v7
	v_add_f32_e32 v8, 0, v1
	v_exp_f32_e32 v11, v11
	v_sub_f32_e32 v12, v12, v7
	v_add_f32_e32 v8, v3, v8
	v_exp_f32_e32 v12, v12
	v_sub_f32_e32 v13, v13, v7
	v_add_f32_e32 v8, v9, v8
	v_exp_f32_e32 v13, v13
	v_sub_f32_e32 v14, v14, v7
	v_add_f32_e32 v8, v10, v8
	v_exp_f32_e32 v14, v14
	v_sub_f32_e32 v15, v15, v7
	v_add_f32_e32 v8, v11, v8
	v_exp_f32_e32 v198, v15
	v_sub_f32_e32 v15, v16, v7
	v_add_f32_e32 v8, v12, v8
	v_exp_f32_e32 v199, v15
	v_sub_f32_e32 v15, v17, v7
	v_add_f32_e32 v8, v13, v8
	v_exp_f32_e32 v200, v15
	v_sub_f32_e32 v15, v18, v7
	v_add_f32_e32 v8, v14, v8
	v_exp_f32_e32 v201, v15
	v_sub_f32_e32 v15, v19, v7
	v_add_f32_e32 v8, v198, v8
	v_exp_f32_e32 v202, v15
	v_sub_f32_e32 v15, v20, v7
	v_add_f32_e32 v8, v199, v8
	v_exp_f32_e32 v203, v15
	v_sub_f32_e32 v15, v21, v7
	v_add_f32_e32 v8, v200, v8
	v_exp_f32_e32 v204, v15
	v_sub_f32_e32 v15, v22, v7
	v_add_f32_e32 v8, v201, v8
	v_exp_f32_e32 v205, v15
	v_sub_f32_e32 v15, v23, v7
	v_add_f32_e32 v8, v202, v8
	v_exp_f32_e32 v206, v15
	v_sub_f32_e32 v15, v24, v7
	v_add_f32_e32 v8, v203, v8
	v_exp_f32_e32 v207, v15
	v_sub_f32_e32 v15, v25, v7
	v_add_f32_e32 v8, v204, v8
	v_exp_f32_e32 v208, v15
	v_sub_f32_e32 v15, v26, v7
	v_add_f32_e32 v8, v205, v8
	v_exp_f32_e32 v209, v15
	v_sub_f32_e32 v15, v27, v7
	v_add_f32_e32 v8, v206, v8
	v_exp_f32_e32 v210, v15
	v_sub_f32_e32 v15, v172, v7
	v_add_f32_e32 v8, v207, v8
	v_exp_f32_e32 v211, v15
	v_sub_f32_e32 v15, v173, v7
	v_add_f32_e32 v8, v208, v8
	v_exp_f32_e32 v173, v15
	v_sub_f32_e32 v15, v189, v7
	v_add_f32_e32 v8, v209, v8
	v_exp_f32_e32 v189, v15
	v_sub_f32_e32 v15, v190, v7
	v_add_f32_e32 v8, v210, v8
	v_exp_f32_e32 v190, v15
	v_sub_f32_e32 v15, v191, v7
	v_add_f32_e32 v8, v211, v8
	v_exp_f32_e32 v191, v15
	v_sub_f32_e32 v15, v192, v7
	v_add_f32_e32 v8, v173, v8
	v_exp_f32_e32 v192, v15
	v_sub_f32_e32 v15, v193, v7
	v_add_f32_e32 v8, v189, v8
	v_exp_f32_e32 v193, v15
	v_sub_f32_e32 v15, v194, v7
	v_add_f32_e32 v8, v190, v8
	v_exp_f32_e32 v194, v15
	v_sub_f32_e32 v15, v195, v7
	v_add_f32_e32 v8, v191, v8
	v_exp_f32_e32 v195, v15
	v_sub_f32_e32 v15, v196, v7
	v_add_f32_e32 v8, v192, v8
	v_exp_f32_e32 v196, v15
	v_sub_f32_e32 v15, v197, v7
	v_add_f32_e32 v8, v193, v8
	v_exp_f32_e32 v197, v15
	v_sub_f32_e32 v4, v4, v7
	v_add_f32_e32 v8, v194, v8
	v_exp_f32_e32 v212, v4
	v_sub_f32_e32 v5, v5, v7
	v_add_f32_e32 v8, v195, v8
	v_exp_f32_e32 v213, v5
	v_sub_f32_e32 v5, v6, v7
	v_add_f32_e32 v8, v196, v8
	v_exp_f32_e32 v214, v5
	v_sub_f32_e32 v0, v0, v7
	v_add_f32_e32 v8, v197, v8
	v_exp_f32_e32 v0, v0
	v_add_f32_e32 v4, v212, v8
	v_add_f32_e32 v4, v213, v4
	v_add_f32_e32 v4, v214, v4
	v_add_f32_e32 v4, v0, v4
	ds_bpermute_b32 v5, v84, v4
	v_bfe_u32 v6, v10, 16, 1
	ds_read2_b64 v[16:19], v168 offset0:192 offset1:196
	v_add3_u32 v8, v10, v6, s88
	v_bfe_u32 v10, v11, 16, 1
	s_waitcnt lgkmcnt(1)
	v_add_f32_e32 v4, v4, v5
	ds_bpermute_b32 v5, v85, v4
	v_bfe_u32 v6, v1, 16, 1
	v_add3_u32 v10, v11, v10, s88
	v_add3_u32 v1, v1, v6, s88
	v_lshrrev_b32_e32 v6, 16, v10
	s_waitcnt lgkmcnt(0)
	v_add_f32_e32 v4, v4, v5
	v_sub_f32_e32 v5, v165, v7
	v_exp_f32_e32 v5, v5
	v_bfe_u32 v7, v3, 16, 1
	v_add3_u32 v3, v3, v7, s88
	v_bfe_u32 v7, v9, 16, 1
	v_add_f32_e32 v172, v5, v4
	v_bfe_u32 v5, v12, 16, 1
	v_add3_u32 v5, v12, v5, s88
	v_bfe_u32 v12, v13, 16, 1
	v_bfe_u32 v4, v14, 16, 1
	v_add3_u32 v12, v13, v12, s88
	v_add3_u32 v7, v9, v7, s88
	v_add3_u32 v4, v14, v4, s88
	v_lshrrev_b32_e32 v9, 16, v7
	v_lshrrev_b32_e32 v7, 16, v12
	ds_read2_b64 v[12:15], v170 offset0:160 offset1:164
	v_and_or_b32 v6, v5, s3, v6
	v_and_or_b32 v5, v8, s3, v9
	ds_read2_b64 v[8:11], v171 offset0:128 offset1:132
	ds_read2_b64 v[20:23], v166 offset0:224 offset1:228
	v_lshrrev_b32_e32 v1, 16, v1
	v_and_or_b32 v7, v4, s3, v7
	v_and_or_b32 v4, v3, s3, v1
	s_waitcnt lgkmcnt(2)
	s_nop 0
	v_mfma_f32_16x16x32_bf16 v[12:15], v[12:15], v[4:7], 0
	v_mfma_f32_16x16x32_bf16 v[16:19], v[16:19], v[4:7], 0
	s_waitcnt lgkmcnt(1)
	v_mfma_f32_16x16x32_bf16 v[8:11], v[8:11], v[4:7], 0
	s_waitcnt lgkmcnt(0)
	v_mfma_f32_16x16x32_bf16 v[4:7], v[20:23], v[4:7], 0
	v_bfe_u32 v20, v201, 16, 1
	v_bfe_u32 v21, v199, 16, 1
	v_add3_u32 v24, v199, v21, s88
	v_add3_u32 v25, v201, v20, s88
	v_bfe_u32 v20, v198, 16, 1
	v_bfe_u32 v21, v200, 16, 1
	v_bfe_u32 v22, v202, 16, 1
	v_bfe_u32 v23, v204, 16, 1
	v_add3_u32 v26, v204, v23, s88
	v_add3_u32 v27, v202, v22, s88
	v_add3_u32 v199, v200, v21, s88
	v_add3_u32 v198, v198, v20, s88
	ds_read2_b64 v[20:23], v171 offset0:136 offset1:140
	ds_read2_b64 v[228:231], v170 offset0:168 offset1:172
	ds_read2_b64 v[232:235], v168 offset0:200 offset1:204
	ds_read2_b64 v[236:239], v166 offset0:232 offset1:236
	v_bfe_u32 v1, v205, 16, 1
	v_bfe_u32 v3, v203, 16, 1
	v_add3_u32 v3, v203, v3, s88
	v_add3_u32 v1, v205, v1, s88
	v_lshrrev_b32_e32 v198, 16, v198
	v_lshrrev_b32_e32 v199, 16, v199
	v_lshrrev_b32_e32 v200, 16, v27
	v_lshrrev_b32_e32 v26, 16, v26
	v_and_or_b32 v27, v1, s3, v26
	v_and_or_b32 v26, v3, s3, v200
	v_and_or_b32 v25, v25, s3, v199
	v_and_or_b32 v24, v24, s3, v198
	s_waitcnt lgkmcnt(3)
; #define LAS __attribute__((address_space(3)))
; __device__ __forceinline__ unsigned pk2(float lo, float hi) { return f2bf(lo) | (f2bf(hi) << 16); }
; __device__ __forceinline__ void st4bf(bf16* p, f32x4 v) { u32x2 w; w.x = pk2(v.x, v.y); w.y = pk2(v.z, v.w); *(u32x2*)p = w; }
; template <bool EARLY>
; __device__ __forceinline__ void attn_ct(const LAS bf16* Kb, const LAS bf16* Vb, const bf16x8 (&qf)[2], float fd, int rl, int l15, int smin, float slope2, float sink2, int lane, f32x4 (&oacc)[4], float& inv) {
;     ...
;     for (int kb = 0; kb < 5; ++kb) {
;         u32x4 pw; pw.x = pk2(sacc[2 * kb][0], sacc[2 * kb][1]); pw.y = pk2(sacc[2 * kb][2], sacc[2 * kb][3]);
;         if (2 * kb + 1 < 9) { pw.z = pk2(sacc[2 * kb + 1][0], sacc[2 * kb + 1][1]); pw.w = pk2(sacc[2 * kb + 1][2], sacc[2 * kb + 1][3]); } else { pw.z = 0u; pw.w = 0u; }
;         const bf16x8 pf = __builtin_bit_cast(bf16x8, pw);
; #pragma unroll
;         for (int dt = 0; dt < 4; ++dt) { const LAS bf16* vp = Vb + dt * 16 * 200 + kb * 32;
;             const u32x2 lo = *(const LAS u32x2*)vp; u32x2 hi = (u32x2){0u, 0u}; if (2 * kb + 1 < 9) hi = *(const LAS u32x2*)(vp + 16);
;             u32x4 w; w.x = lo.x; w.y = lo.y; w.z = hi.x; w.w = hi.y; const bf16x8 vf = __builtin_bit_cast(bf16x8, w);
;             oacc[dt] = __builtin_amdgcn_mfma_f32_16x16x32_bf16(vf, pf, oacc[dt], 0, 0, 0); }
;         __builtin_amdgcn_sched_barrier(0);
;     }
; __device__ __forceinline__ void attn_phase(const Params& p, int layer, LAS unsigned char* lds, int tid) {
;     ...
;             if (t < L) {
; #pragma unroll
;                 for (int dt = 0; dt < 4; ++dt) st4bf(YC + (mb + t) * 512 + hq * 64 + dt * 16 + quad * 4, oacc[dt] * inv); }
	s_nop 0
	v_mfma_f32_16x16x32_bf16 v[8:11], v[20:23], v[24:27], v[8:11]
	s_waitcnt lgkmcnt(2)
	v_mfma_f32_16x16x32_bf16 v[12:15], v[228:231], v[24:27], v[12:15]
	s_waitcnt lgkmcnt(1)
	v_mfma_f32_16x16x32_bf16 v[16:19], v[232:235], v[24:27], v[16:19]
	s_waitcnt lgkmcnt(0)
	v_mfma_f32_16x16x32_bf16 v[4:7], v[236:239], v[24:27], v[4:7]
	v_bfe_u32 v20, v209, 16, 1
	v_bfe_u32 v21, v207, 16, 1
	v_bfe_u32 v1, v189, 16, 1
	v_add3_u32 v24, v207, v21, s88
	v_add3_u32 v25, v209, v20, s88
	v_bfe_u32 v20, v206, 16, 1
	v_bfe_u32 v21, v208, 16, 1
	v_bfe_u32 v22, v210, 16, 1
	v_bfe_u32 v23, v173, 16, 1
	v_add3_u32 v1, v189, v1, s88
	v_add3_u32 v26, v173, v23, s88
	v_add3_u32 v27, v210, v22, s88
	v_add3_u32 v173, v208, v21, s88
	v_add3_u32 v189, v206, v20, s88
	ds_read2_b64 v[20:23], v171 offset0:144 offset1:148
	ds_read2_b64 v[228:231], v170 offset0:176 offset1:180
	ds_read2_b64 v[232:235], v168 offset0:208 offset1:212
	ds_read2_b64 v[236:239], v166 offset0:240 offset1:244
	v_bfe_u32 v3, v211, 16, 1
	v_add3_u32 v3, v211, v3, s88
	v_lshrrev_b32_e32 v189, 16, v189
	v_lshrrev_b32_e32 v173, 16, v173
	v_lshrrev_b32_e32 v198, 16, v27
	v_lshrrev_b32_e32 v26, 16, v26
	v_and_or_b32 v27, v1, s3, v26
	v_and_or_b32 v26, v3, s3, v198
	v_and_or_b32 v25, v25, s3, v173
	v_and_or_b32 v24, v24, s3, v189
	s_waitcnt lgkmcnt(3)
	s_nop 0
	v_mfma_f32_16x16x32_bf16 v[8:11], v[20:23], v[24:27], v[8:11]
	s_waitcnt lgkmcnt(2)
	v_mfma_f32_16x16x32_bf16 v[12:15], v[228:231], v[24:27], v[12:15]
	s_waitcnt lgkmcnt(1)
	v_mfma_f32_16x16x32_bf16 v[16:19], v[232:235], v[24:27], v[16:19]
	s_waitcnt lgkmcnt(0)
	v_mfma_f32_16x16x32_bf16 v[4:7], v[236:239], v[24:27], v[4:7]
	v_bfe_u32 v20, v193, 16, 1
	v_bfe_u32 v21, v191, 16, 1
	v_add3_u32 v24, v191, v21, s88
	v_add3_u32 v25, v193, v20, s88
	v_bfe_u32 v20, v190, 16, 1
	v_bfe_u32 v21, v192, 16, 1
	v_bfe_u32 v22, v194, 16, 1
	v_bfe_u32 v23, v196, 16, 1
	v_add3_u32 v26, v196, v23, s88
	v_add3_u32 v27, v194, v22, s88
	v_add3_u32 v173, v192, v21, s88
	v_add3_u32 v189, v190, v20, s88
	ds_read2_b64 v[20:23], v171 offset0:152 offset1:156
	ds_read2_b64 v[228:231], v170 offset0:184 offset1:188
	ds_read2_b64 v[232:235], v168 offset0:216 offset1:220
	ds_read2_b64 v[236:239], v166 offset0:248 offset1:252
	v_bfe_u32 v1, v197, 16, 1
	v_bfe_u32 v3, v195, 16, 1
	v_add3_u32 v3, v195, v3, s88
	v_add3_u32 v1, v197, v1, s88
	v_lshrrev_b32_e32 v171, 16, v189
	v_lshrrev_b32_e32 v173, 16, v173
	v_lshrrev_b32_e32 v189, 16, v27
	v_lshrrev_b32_e32 v26, 16, v26
	v_and_or_b32 v27, v1, s3, v26
	v_and_or_b32 v26, v3, s3, v189
	v_and_or_b32 v25, v25, s3, v173
	v_and_or_b32 v24, v24, s3, v171
	s_waitcnt lgkmcnt(3)
	s_nop 0
	v_mfma_f32_16x16x32_bf16 v[8:11], v[20:23], v[24:27], v[8:11]
	s_waitcnt lgkmcnt(2)
	v_mfma_f32_16x16x32_bf16 v[12:15], v[228:231], v[24:27], v[12:15]
	s_waitcnt lgkmcnt(1)
	v_mfma_f32_16x16x32_bf16 v[190:193], v[232:235], v[24:27], v[16:19]
	s_nop 2
	s_waitcnt lgkmcnt(0)
	v_mfma_f32_16x16x32_bf16 v[4:7], v[236:239], v[24:27], v[4:7]
	v_and_b32_sdwa v1, v0, v174 dst_sel:DWORD dst_unused:UNUSED_PAD src0_sel:WORD_1 src1_sel:DWORD
	v_and_b32_sdwa v3, v213, v174 dst_sel:DWORD dst_unused:UNUSED_PAD src0_sel:WORD_1 src1_sel:DWORD
	v_add3_u32 v0, v0, v1, s88
	v_add3_u32 v1, v213, v3, s88
	v_and_b32_e32 v3, 0xffff0000, v1
	v_and_b32_sdwa v1, v214, v174 dst_sel:DWORD dst_unused:UNUSED_PAD src0_sel:WORD_1 src1_sel:DWORD
	v_and_b32_sdwa v16, v212, v174 dst_sel:DWORD dst_unused:UNUSED_PAD src0_sel:WORD_1 src1_sel:DWORD
	v_and_b32_e32 v0, 0xffff0000, v0
	v_add3_u32 v16, v212, v16, s88
	v_add3_u32 v1, v214, v1, s88
	v_or_b32_sdwa v1, v0, v1 dst_sel:DWORD dst_unused:UNUSED_PAD src0_sel:DWORD src1_sel:WORD_1
	v_or_b32_sdwa v0, v3, v16 dst_sel:DWORD dst_unused:UNUSED_PAD src0_sel:DWORD src1_sel:WORD_1
	ds_read_b64 v[16:17], v39 offset:27904
	ds_read_b64 v[228:229], v39 offset:34304
	ds_read_b64 v[232:233], v39 offset:40704
	ds_read_b64 v[236:237], v39 offset:47104
	v_mov_b32_e32 v18, v2
	v_mov_b32_e32 v19, v2
	v_mov_b32_e32 v3, v2
	v_mov_b32_e32 v230, v2
	v_mov_b32_e32 v231, v2
	v_mov_b32_e32 v234, v2
	v_mov_b32_e32 v235, v2
	v_mov_b32_e32 v238, v2
	v_mov_b32_e32 v239, v2
	s_waitcnt lgkmcnt(3)
	s_nop 0
	v_mfma_f32_16x16x32_bf16 v[16:19], v[16:19], v[0:3], v[8:11]
	s_waitcnt lgkmcnt(2)
	v_mfma_f32_16x16x32_bf16 v[20:23], v[228:231], v[0:3], v[12:15]
	s_waitcnt lgkmcnt(1)
	v_mfma_f32_16x16x32_bf16 v[12:15], v[232:235], v[0:3], v[190:193]
	s_waitcnt lgkmcnt(0)
	v_mfma_f32_16x16x32_bf16 v[24:27], v[236:239], v[0:3], v[4:7]
	s_movk_i32 s7, 0x1010
	v_cmp_gt_i32_e32 vcc, s7, v38
	s_and_saveexec_b64 s[10:11], vcc
	s_cbranch_execz .LBB0_505
